# v55 + P7 epilogue: the 7 dependent per-row-block statistic loads issued with the first one (immediate offsets), their wait(0)s removed
# baseline (speedup 1.0000x reference)
.LBB0_1313:
	v_cvt_f32_i32_e32 v173, v127
	v_cvt_f32_i32_e32 v172, v126
	v_cvt_f32_i32_e32 v171, v125
	v_cvt_f32_i32_e32 v170, v124
	v_cvt_f32_i32_e32 v169, v123
	v_cvt_f32_i32_e32 v168, v122
	v_cvt_f32_i32_e32 v167, v121
	v_cvt_f32_i32_e32 v166, v120
	v_cvt_f32_i32_e32 v125, v109
	v_cvt_f32_i32_e32 v124, v108
	v_cvt_f32_i32_e32 v127, v111
	v_cvt_f32_i32_e32 v126, v110
	v_cvt_f32_i32_e32 v121, v101
	v_cvt_f32_i32_e32 v120, v100
	v_cvt_f32_i32_e32 v123, v103
	v_cvt_f32_i32_e32 v122, v102
	v_cvt_f32_i32_e32 v165, v119
	v_cvt_f32_i32_e32 v164, v118
	v_cvt_f32_i32_e32 v163, v117
	v_cvt_f32_i32_e32 v162, v116
	v_cvt_f32_i32_e32 v161, v115
	v_cvt_f32_i32_e32 v160, v114
	v_cvt_f32_i32_e32 v159, v113
	v_cvt_f32_i32_e32 v158, v112
	v_cvt_f32_i32_e32 v117, v93
	v_cvt_f32_i32_e32 v116, v92
	v_cvt_f32_i32_e32 v119, v95
	v_cvt_f32_i32_e32 v118, v94
	v_cvt_f32_i32_e32 v111, v85
	v_cvt_f32_i32_e32 v110, v84
	v_cvt_f32_i32_e32 v115, v87
	v_cvt_f32_i32_e32 v114, v86
	v_cvt_f32_i32_e32 v157, v107
	v_cvt_f32_i32_e32 v156, v106
	v_cvt_f32_i32_e32 v155, v105
	v_cvt_f32_i32_e32 v154, v104
	v_cvt_f32_i32_e32 v153, v99
	v_cvt_f32_i32_e32 v152, v98
	v_cvt_f32_i32_e32 v151, v97
	v_cvt_f32_i32_e32 v150, v96
	v_cvt_f32_i32_e32 v109, v77
	v_cvt_f32_i32_e32 v108, v76
	v_cvt_f32_i32_e32 v113, v79
	v_cvt_f32_i32_e32 v112, v78
	v_cvt_f32_i32_e32 v103, v73
	v_cvt_f32_i32_e32 v102, v72
	v_cvt_f32_i32_e32 v107, v75
	v_cvt_f32_i32_e32 v106, v74
	v_cvt_f32_i32_e32 v149, v91
	v_cvt_f32_i32_e32 v148, v90
	v_cvt_f32_i32_e32 v147, v89
	v_cvt_f32_i32_e32 v146, v88
	v_cvt_f32_i32_e32 v145, v83
	v_cvt_f32_i32_e32 v144, v82
	v_cvt_f32_i32_e32 v143, v81
	v_cvt_f32_i32_e32 v142, v80
	v_cvt_f32_i32_e32 v101, v69
	v_cvt_f32_i32_e32 v100, v68
	v_cvt_f32_i32_e32 v105, v71
	v_cvt_f32_i32_e32 v104, v70
	v_cvt_f32_i32_e32 v97, v65
	v_cvt_f32_i32_e32 v96, v64
	v_cvt_f32_i32_e32 v99, v67
	v_cvt_f32_i32_e32 v98, v66
	s_cmp_lt_i32 s90, 0
	s_mov_b64 s[58:59], -1
	s_cbranch_scc0 .LBB0_1316
	v_lshl_add_u32 v174, s54, 8, v182
	v_lshl_add_u32 v176, s56, 8, v180
	v_ashrrev_i32_e32 v175, 31, v174
	v_ashrrev_i32_e32 v177, 31, v176
	v_lshlrev_b64 v[64:65], 2, v[174:175]
	v_lshl_add_u64 v[68:69], v[176:177], 3, s[0:1]
	v_lshl_add_u64 v[66:67], s[18:19], 0, v[64:65]
	global_load_dwordx2 v[178:179], v[68:69], off
	global_load_dwordx2 v[220:221], v[68:69], off offset:128
	global_load_dwordx2 v[222:223], v[68:69], off offset:256
	global_load_dwordx2 v[224:225], v[68:69], off offset:384
	global_load_dwordx2 v[226:227], v[68:69], off offset:1024
	global_load_dwordx2 v[228:229], v[68:69], off offset:1152
	global_load_dwordx2 v[230:231], v[68:69], off offset:1280
	global_load_dwordx2 v[232:233], v[68:69], off offset:1408
	global_load_dwordx4 v[92:95], v[66:67], off
	global_load_dwordx4 v[84:87], v[66:67], off offset:16
	global_load_dwordx4 v[76:79], v[66:67], off offset:512
	s_nop 0
	global_load_dwordx4 v[68:71], v[66:67], off offset:528
	v_lshl_add_u64 v[64:65], s[34:35], 0, v[64:65]
	global_load_dwordx4 v[88:91], v[64:65], off
	global_load_dwordx4 v[80:83], v[64:65], off offset:16
	global_load_dwordx4 v[72:75], v[64:65], off offset:512
	s_nop 0
	global_load_dwordx4 v[64:67], v[64:65], off offset:528
	v_pk_mul_f32 v[184:185], v[126:127], s[6:7] op_sel_hi:[1,0]
	v_pk_mul_f32 v[186:187], v[124:125], s[6:7] op_sel_hi:[1,0]
	v_pk_mul_f32 v[188:189], v[122:123], s[6:7] op_sel_hi:[1,0]
	v_pk_mul_f32 v[190:191], v[120:121], s[6:7] op_sel_hi:[1,0]
	s_lshl_b32 s24, s54, 7
	v_subrev_u32_e32 v174, s24, v174
	v_ashrrev_i32_e32 v175, 31, v174
	s_waitcnt vmcnt(0)
	v_pk_mul_f32 v[192:193], v[94:95], v[178:179] op_sel_hi:[1,0]
	v_pk_mul_f32 v[194:195], v[92:93], v[178:179] op_sel_hi:[1,0]
	v_pk_mul_f32 v[198:199], v[84:85], v[178:179] op_sel_hi:[1,0]
	v_pk_mul_f32 v[196:197], v[86:87], v[178:179] op_sel_hi:[1,0]
	v_pk_fma_f32 v[194:195], v[170:171], s[6:7], v[194:195] op_sel_hi:[1,0,1] neg_lo:[0,0,1] neg_hi:[0,0,1]
	v_pk_fma_f32 v[192:193], v[172:173], s[6:7], v[192:193] op_sel_hi:[1,0,1] neg_lo:[0,0,1] neg_hi:[0,0,1]
	v_pk_fma_f32 v[198:199], v[166:167], s[6:7], v[198:199] op_sel_hi:[1,0,1] neg_lo:[0,0,1] neg_hi:[0,0,1]
	v_pk_fma_f32 v[196:197], v[168:169], s[6:7], v[196:197] op_sel_hi:[1,0,1] neg_lo:[0,0,1] neg_hi:[0,0,1]
	v_pk_fma_f32 v[192:193], v[178:179], v[192:193], v[90:91] op_sel:[1,0,0]
	v_pk_fma_f32 v[194:195], v[178:179], v[194:195], v[88:89] op_sel:[1,0,0]
	v_pk_fma_f32 v[198:199], v[178:179], v[198:199], v[80:81] op_sel:[1,0,0]
	v_fma_f32 v200, -v77, v178, v187
	v_fma_f32 v202, -v69, v178, v191
	v_fma_f32 v204, -v70, v178, v188
	v_fma_f32 v206, -v79, v178, v185
	v_pk_fma_f32 v[196:197], v[178:179], v[196:197], v[82:83] op_sel:[1,0,0]
	v_mul_f32_e32 v177, 0xbfb8aa3b, v194
	v_mul_f32_e32 v185, 0xbfb8aa3b, v198
	v_mul_f32_e32 v187, 0xbfb8aa3b, v195
	v_mul_f32_e32 v188, 0xbfb8aa3b, v199
	v_mul_f32_e32 v191, 0xbfb8aa3b, v192
	v_mul_f32_e32 v201, 0xbfb8aa3b, v196
	v_exp_f32_e32 v177, v177
	v_exp_f32_e32 v185, v185
	v_exp_f32_e32 v187, v187
	v_exp_f32_e32 v188, v188
	v_exp_f32_e32 v191, v191
	v_exp_f32_e32 v201, v201
	v_mul_f32_e32 v203, 0xbfb8aa3b, v197
	v_exp_f32_e32 v216, v203
	v_add_f32_e32 v177, 1.0, v177
	v_add_f32_e32 v185, 1.0, v185
	v_add_f32_e32 v203, 1.0, v187
	v_add_f32_e32 v188, 1.0, v188
	v_add_f32_e32 v205, 1.0, v191
	v_add_f32_e32 v207, 1.0, v201
	v_rcp_f32_e32 v187, v177
	v_rcp_f32_e32 v191, v185
	v_rcp_f32_e32 v201, v203
	v_rcp_f32_e32 v203, v188
	v_rcp_f32_e32 v185, v205
	v_fma_f32 v186, -v76, v178, v186
	v_fma_f32 v190, -v68, v178, v190
	v_fma_f32 v184, -v78, v178, v184
	v_pk_mov_b32 v[208:209], v[178:179], v[194:195] op_sel:[1,0]
	v_pk_mov_b32 v[210:211], v[178:179], v[198:199] op_sel:[1,0]
	v_mov_b32_e32 v194, v179
	v_mov_b32_e32 v198, v179
	v_pk_mov_b32 v[212:213], v[178:179], v[192:193] op_sel:[1,0]
	v_pk_mov_b32 v[214:215], v[178:179], v[196:197] op_sel:[1,0]
	v_mul_f32_e32 v196, 0xbfb8aa3b, v193
	v_pk_mul_f32 v[186:187], v[208:209], v[186:187]
	v_pk_mul_f32 v[190:191], v[210:211], v[190:191]
	v_pk_mul_f32 v[194:195], v[194:195], v[200:201]
	v_pk_mul_f32 v[198:199], v[198:199], v[202:203]
	v_pk_mul_f32 v[184:185], v[212:213], v[184:185]
	v_exp_f32_e32 v196, v196
	v_add_f32_e32 v177, v72, v186
	v_add_f32_e32 v186, v64, v190
	v_add_f32_e32 v188, v73, v194
	v_add_f32_e32 v190, v65, v198
	v_add_f32_e32 v184, v74, v184
	v_mul_f32_e32 v177, v177, v187
	v_mul_f32_e32 v187, v188, v195
	v_mul_f32_e32 v188, v190, v199
	v_mul_f32_e32 v190, v184, v185
	v_add_f32_e32 v184, 1.0, v216
	v_rcp_f32_e32 v185, v184
	v_add_f32_e32 v196, 1.0, v196
	v_rcp_f32_e32 v205, v207
	v_rcp_f32_e32 v207, v196
	v_fma_f32 v184, -v71, v178, v189
	v_mov_b32_e32 v196, v179
	v_mov_b32_e32 v192, v179
	v_pk_mul_f32 v[178:179], v[196:197], v[184:185]
	v_mul_f32_e32 v186, v186, v191
	v_add_f32_e32 v178, v67, v178
	v_mul_f32_e32 v178, v178, v179
	v_mul_f32_e32 v177, 0x41000000, v177
	v_mul_f32_e32 v179, 0x41000000, v187
	v_mov_b32_e32 v184, 0
	v_cvt_pk_fp8_f32 v184, v177, v179
	v_mul_f32_e32 v177, 0x41000000, v186
	v_mul_f32_e32 v179, 0x41000000, v188
	v_mov_b32_e32 v185, 0
	v_pk_mul_f32 v[200:201], v[214:215], v[204:205]
	v_pk_mul_f32 v[192:193], v[192:193], v[206:207]
	v_cvt_pk_fp8_f32 v185, v177, v179
	v_add_f32_e32 v194, v66, v200
	v_add_f32_e32 v192, v75, v192
	v_mul_f32_e32 v191, v194, v201
	v_mul_f32_e32 v192, v192, v193
	v_mul_f32_e32 v187, 0x41000000, v190
	v_mul_f32_e32 v189, 0x41000000, v192
	v_mul_f32_e32 v177, 0x41000000, v191
	v_mul_f32_e32 v178, 0x41000000, v178
	v_cvt_pk_fp8_f32 v184, v187, v189 op_sel:[0,0,1]
	v_cvt_pk_fp8_f32 v185, v177, v178 op_sel:[0,0,1]
	v_mov_b64_e32 v[178:179], s[16:17]
	v_mad_i64_i32 v[186:187], s[24:25], v176, s82, v[178:179]
	v_lshl_add_u64 v[186:187], v[186:187], 0, v[174:175]
	global_store_dwordx2 v[186:187], v[184:185], off
	v_or_b32_e32 v184, 16, v176
	v_ashrrev_i32_e32 v185, 31, v184
	v_mov_b32_e32 v186, v220
	v_mov_b32_e32 v187, v221
	v_pk_mul_f32 v[188:189], v[118:119], s[6:7] op_sel_hi:[1,0]
	v_pk_mul_f32 v[192:193], v[114:115], s[6:7] op_sel_hi:[1,0]
	v_pk_mul_f32 v[190:191], v[116:117], s[6:7] op_sel_hi:[1,0]
	v_pk_mul_f32 v[194:195], v[110:111], s[6:7] op_sel_hi:[1,0]
	v_pk_mul_f32 v[196:197], v[94:95], v[186:187] op_sel_hi:[1,0]
	v_pk_mul_f32 v[198:199], v[92:93], v[186:187] op_sel_hi:[1,0]
	v_pk_mul_f32 v[202:203], v[84:85], v[186:187] op_sel_hi:[1,0]
	v_pk_fma_f32 v[198:199], v[162:163], s[6:7], v[198:199] op_sel_hi:[1,0,1] neg_lo:[0,0,1] neg_hi:[0,0,1]
	v_pk_fma_f32 v[196:197], v[164:165], s[6:7], v[196:197] op_sel_hi:[1,0,1] neg_lo:[0,0,1] neg_hi:[0,0,1]
	v_pk_mul_f32 v[200:201], v[86:87], v[186:187] op_sel_hi:[1,0]
	v_pk_fma_f32 v[202:203], v[158:159], s[6:7], v[202:203] op_sel_hi:[1,0,1] neg_lo:[0,0,1] neg_hi:[0,0,1]
	v_pk_fma_f32 v[196:197], v[186:187], v[196:197], v[90:91] op_sel:[1,0,0]
	v_pk_fma_f32 v[198:199], v[186:187], v[198:199], v[88:89] op_sel:[1,0,0]
	v_fma_f32 v208, -v70, v186, v192
	v_fma_f32 v210, -v79, v186, v189
	v_pk_fma_f32 v[200:201], v[160:161], s[6:7], v[200:201] op_sel_hi:[1,0,1] neg_lo:[0,0,1] neg_hi:[0,0,1]
	v_pk_fma_f32 v[202:203], v[186:187], v[202:203], v[80:81] op_sel:[1,0,0]
	v_mul_f32_e32 v189, 0xbfb8aa3b, v199
	v_mul_f32_e32 v192, 0xbfb8aa3b, v196
	v_pk_fma_f32 v[200:201], v[186:187], v[200:201], v[82:83] op_sel:[1,0,0]
	v_mul_f32_e32 v177, 0xbfb8aa3b, v198
	v_mul_f32_e32 v185, 0xbfb8aa3b, v202
	v_exp_f32_e32 v189, v189
	v_exp_f32_e32 v192, v192
	v_fma_f32 v204, -v77, v186, v191
	v_fma_f32 v206, -v69, v186, v195
	v_mul_f32_e32 v191, 0xbfb8aa3b, v203
	v_mul_f32_e32 v195, 0xbfb8aa3b, v200
	v_exp_f32_e32 v177, v177
	v_exp_f32_e32 v185, v185
	v_exp_f32_e32 v191, v191
	v_exp_f32_e32 v195, v195
	v_add_f32_e32 v189, 1.0, v189
	v_add_f32_e32 v192, 1.0, v192
	v_add_f32_e32 v177, 1.0, v177
	v_add_f32_e32 v185, 1.0, v185
	v_rcp_f32_e32 v205, v189
	v_rcp_f32_e32 v189, v192
	v_pk_mov_b32 v[218:219], v[186:187], v[200:201] op_sel:[1,0]
	v_add_f32_e32 v200, 1.0, v191
	v_add_f32_e32 v209, 1.0, v195
	v_rcp_f32_e32 v191, v177
	v_rcp_f32_e32 v195, v185
	v_fma_f32 v188, -v78, v186, v188
	v_pk_mov_b32 v[216:217], v[186:187], v[196:197] op_sel:[1,0]
	v_fma_f32 v190, -v76, v186, v190
	v_fma_f32 v194, -v68, v186, v194
	v_pk_mov_b32 v[212:213], v[186:187], v[198:199] op_sel:[1,0]
	v_pk_mov_b32 v[214:215], v[186:187], v[202:203] op_sel:[1,0]
	v_mov_b32_e32 v198, v187
	v_pk_mul_f32 v[188:189], v[216:217], v[188:189]
	v_pk_mul_f32 v[190:191], v[212:213], v[190:191]
	v_pk_mul_f32 v[194:195], v[214:215], v[194:195]
	v_pk_mul_f32 v[198:199], v[198:199], v[204:205]
	v_add_f32_e32 v188, v74, v188
	v_mul_f32_e32 v196, 0xbfb8aa3b, v197
	v_add_f32_e32 v177, v72, v190
	v_add_f32_e32 v185, v64, v194
	v_add_f32_e32 v190, v73, v198
	v_mul_f32_e32 v198, v188, v189
	v_mul_f32_e32 v188, 0xbfb8aa3b, v201
	v_exp_f32_e32 v196, v196
	v_mul_f32_e32 v185, v185, v195
	v_mul_f32_e32 v195, v190, v199
	v_exp_f32_e32 v190, v188
	v_add_f32_e32 v196, 1.0, v196
	v_rcp_f32_e32 v207, v200
	v_rcp_f32_e32 v211, v196
	v_add_f32_e32 v190, 1.0, v190
	v_mul_f32_e32 v177, v177, v191
	v_rcp_f32_e32 v191, v190
	v_mov_b32_e32 v202, v187
	v_mov_b32_e32 v196, v187
	v_fma_f32 v190, -v71, v186, v193
	v_mov_b32_e32 v200, v187
	v_rcp_f32_e32 v209, v209
	v_pk_mul_f32 v[202:203], v[202:203], v[206:207]
	v_pk_mul_f32 v[188:189], v[196:197], v[210:211]
	v_pk_mul_f32 v[186:187], v[200:201], v[190:191]
	v_add_f32_e32 v192, v65, v202
	v_add_f32_e32 v188, v75, v188
	v_add_f32_e32 v186, v67, v186
	v_mul_f32_e32 v192, v192, v203
	v_mul_f32_e32 v188, v188, v189
	v_mul_f32_e32 v189, v186, v187
	v_mul_f32_e32 v177, 0x41000000, v177
	v_mul_f32_e32 v187, 0x41000000, v195
	v_mov_b32_e32 v186, 0
	v_cvt_pk_fp8_f32 v186, v177, v187
	v_mul_f32_e32 v177, 0x41000000, v185
	v_mul_f32_e32 v185, 0x41000000, v192
	v_mov_b32_e32 v187, 0
	v_pk_mul_f32 v[204:205], v[218:219], v[208:209]
	v_cvt_pk_fp8_f32 v187, v177, v185
	v_add_f32_e32 v194, v66, v204
	v_mul_f32_e32 v194, v194, v205
	v_mul_f32_e32 v190, 0x41000000, v198
	v_mul_f32_e32 v188, 0x41000000, v188
	v_mul_f32_e32 v177, 0x41000000, v194
	v_mul_f32_e32 v185, 0x41000000, v189
	v_cvt_pk_fp8_f32 v186, v190, v188 op_sel:[0,0,1]
	v_cvt_pk_fp8_f32 v187, v177, v185 op_sel:[0,0,1]
	v_mad_i64_i32 v[184:185], s[24:25], v184, s82, v[178:179]
	v_lshl_add_u64 v[184:185], v[184:185], 0, v[174:175]
	global_store_dwordx2 v[184:185], v[186:187], off
	v_or_b32_e32 v184, 32, v176
	v_ashrrev_i32_e32 v185, 31, v184
	v_mov_b32_e32 v186, v222
	v_mov_b32_e32 v187, v223
	v_pk_mul_f32 v[188:189], v[112:113], s[6:7] op_sel_hi:[1,0]
	v_pk_mul_f32 v[194:195], v[102:103], s[6:7] op_sel_hi:[1,0]
	v_pk_mul_f32 v[190:191], v[108:109], s[6:7] op_sel_hi:[1,0]
	v_pk_mul_f32 v[192:193], v[106:107], s[6:7] op_sel_hi:[1,0]
	v_pk_mul_f32 v[198:199], v[92:93], v[186:187] op_sel_hi:[1,0]
	v_pk_mul_f32 v[202:203], v[84:85], v[186:187] op_sel_hi:[1,0]
	v_pk_mul_f32 v[200:201], v[86:87], v[186:187] op_sel_hi:[1,0]
	v_pk_fma_f32 v[198:199], v[154:155], s[6:7], v[198:199] op_sel_hi:[1,0,1] neg_lo:[0,0,1] neg_hi:[0,0,1]
	v_pk_fma_f32 v[202:203], v[150:151], s[6:7], v[202:203] op_sel_hi:[1,0,1] neg_lo:[0,0,1] neg_hi:[0,0,1]
	v_pk_fma_f32 v[200:201], v[152:153], s[6:7], v[200:201] op_sel_hi:[1,0,1] neg_lo:[0,0,1] neg_hi:[0,0,1]
	v_pk_fma_f32 v[198:199], v[186:187], v[198:199], v[88:89] op_sel:[1,0,0]
	v_pk_fma_f32 v[202:203], v[186:187], v[202:203], v[80:81] op_sel:[1,0,0]
	v_fma_f32 v208, -v78, v186, v188
	v_pk_fma_f32 v[200:201], v[186:187], v[200:201], v[82:83] op_sel:[1,0,0]
	v_mul_f32_e32 v185, 0xbfb8aa3b, v202
	v_mul_f32_e32 v188, 0xbfb8aa3b, v199
	v_fma_f32 v206, -v69, v186, v195
	v_mul_f32_e32 v177, 0xbfb8aa3b, v198
	v_mul_f32_e32 v195, 0xbfb8aa3b, v200
	v_exp_f32_e32 v185, v185
	v_exp_f32_e32 v188, v188
	v_fma_f32 v204, -v77, v186, v191
	v_mul_f32_e32 v191, 0xbfb8aa3b, v203
	v_exp_f32_e32 v177, v177
	v_exp_f32_e32 v195, v195
	v_exp_f32_e32 v191, v191
	v_pk_mul_f32 v[196:197], v[94:95], v[186:187] op_sel_hi:[1,0]
	v_add_f32_e32 v185, 1.0, v185
	v_pk_fma_f32 v[196:197], v[156:157], s[6:7], v[196:197] op_sel_hi:[1,0,1] neg_lo:[0,0,1] neg_hi:[0,0,1]
	v_add_f32_e32 v188, 1.0, v188
	v_pk_fma_f32 v[196:197], v[186:187], v[196:197], v[90:91] op_sel:[1,0,0]
	v_add_f32_e32 v177, 1.0, v177
	v_add_f32_e32 v211, 1.0, v195
	v_rcp_f32_e32 v195, v185
	v_rcp_f32_e32 v205, v188
	v_fma_f32 v210, -v70, v186, v192
	v_mul_f32_e32 v192, 0xbfb8aa3b, v196
	v_pk_mov_b32 v[216:217], v[186:187], v[196:197] op_sel:[1,0]
	v_pk_mov_b32 v[218:219], v[186:187], v[200:201] op_sel:[1,0]
	v_mul_f32_e32 v196, 0xbfb8aa3b, v197
	v_add_f32_e32 v200, 1.0, v191
	v_rcp_f32_e32 v191, v177
	v_exp_f32_e32 v196, v196
	v_fma_f32 v194, -v68, v186, v194
	v_pk_mov_b32 v[212:213], v[186:187], v[198:199] op_sel:[1,0]
	v_pk_mov_b32 v[214:215], v[186:187], v[202:203] op_sel:[1,0]
	v_mov_b32_e32 v198, v187
	v_fma_f32 v190, -v76, v186, v190
	v_pk_mul_f32 v[194:195], v[214:215], v[194:195]
	v_pk_mul_f32 v[198:199], v[198:199], v[204:205]
	v_rcp_f32_e32 v207, v200
	v_pk_mul_f32 v[190:191], v[212:213], v[190:191]
	v_add_f32_e32 v185, v64, v194
	v_add_f32_e32 v188, v73, v198
	v_add_f32_e32 v177, v72, v190
	v_mul_f32_e32 v185, v185, v195
	v_mul_f32_e32 v195, v188, v199
	v_add_f32_e32 v188, 1.0, v196
	v_mul_f32_e32 v177, v177, v191
	v_rcp_f32_e32 v191, v188
	v_mul_f32_e32 v188, 0xbfb8aa3b, v201
	v_mov_b32_e32 v202, v187
	v_exp_f32_e32 v199, v188
	v_pk_mul_f32 v[202:203], v[202:203], v[206:207]
	v_mov_b32_e32 v196, v187
	v_add_f32_e32 v190, v65, v202
	v_mul_f32_e32 v198, v190, v203
	v_fma_f32 v190, -v79, v186, v189
	v_exp_f32_e32 v192, v192
	v_pk_mul_f32 v[188:189], v[196:197], v[190:191]
	v_add_f32_e32 v190, 1.0, v199
	v_rcp_f32_e32 v191, v190
	v_add_f32_e32 v192, 1.0, v192
	v_fma_f32 v190, -v71, v186, v193
	v_mov_b32_e32 v200, v187
	v_rcp_f32_e32 v209, v192
	v_rcp_f32_e32 v211, v211
	v_pk_mul_f32 v[186:187], v[200:201], v[190:191]
	v_add_f32_e32 v188, v75, v188
	v_add_f32_e32 v186, v67, v186
	v_mul_f32_e32 v188, v188, v189
	v_mul_f32_e32 v189, v186, v187
	v_mul_f32_e32 v177, 0x41000000, v177
	v_mul_f32_e32 v187, 0x41000000, v195
	v_mov_b32_e32 v186, 0
	v_cvt_pk_fp8_f32 v186, v177, v187
	v_mul_f32_e32 v177, 0x41000000, v185
	v_mul_f32_e32 v185, 0x41000000, v198
	v_mov_b32_e32 v187, 0
	v_pk_mul_f32 v[204:205], v[216:217], v[208:209]
	v_pk_mul_f32 v[206:207], v[218:219], v[210:211]
	v_cvt_pk_fp8_f32 v187, v177, v185
	v_add_f32_e32 v192, v74, v204
	v_add_f32_e32 v194, v66, v206
	v_mul_f32_e32 v192, v192, v205
	v_mul_f32_e32 v194, v194, v207
	v_mul_f32_e32 v190, 0x41000000, v192
	v_mul_f32_e32 v188, 0x41000000, v188
	v_mul_f32_e32 v177, 0x41000000, v194
	v_mul_f32_e32 v185, 0x41000000, v189
	v_cvt_pk_fp8_f32 v186, v190, v188 op_sel:[0,0,1]
	v_cvt_pk_fp8_f32 v187, v177, v185 op_sel:[0,0,1]
	v_mad_i64_i32 v[184:185], s[24:25], v184, s82, v[178:179]
	v_lshl_add_u64 v[184:185], v[184:185], 0, v[174:175]
	global_store_dwordx2 v[184:185], v[186:187], off
	v_or_b32_e32 v184, 48, v176
	v_ashrrev_i32_e32 v185, 31, v184
	v_mov_b32_e32 v186, v224
	v_mov_b32_e32 v187, v225
	v_pk_mul_f32 v[188:189], v[104:105], s[6:7] op_sel_hi:[1,0]
	v_pk_mul_f32 v[194:195], v[96:97], s[6:7] op_sel_hi:[1,0]
	v_pk_mul_f32 v[190:191], v[100:101], s[6:7] op_sel_hi:[1,0]
	v_pk_mul_f32 v[192:193], v[98:99], s[6:7] op_sel_hi:[1,0]
	v_pk_mul_f32 v[198:199], v[92:93], v[186:187] op_sel_hi:[1,0]
	v_pk_mul_f32 v[202:203], v[84:85], v[186:187] op_sel_hi:[1,0]
	v_pk_fma_f32 v[198:199], v[146:147], s[6:7], v[198:199] op_sel_hi:[1,0,1] neg_lo:[0,0,1] neg_hi:[0,0,1]
	v_pk_mul_f32 v[200:201], v[86:87], v[186:187] op_sel_hi:[1,0]
	v_pk_fma_f32 v[202:203], v[142:143], s[6:7], v[202:203] op_sel_hi:[1,0,1] neg_lo:[0,0,1] neg_hi:[0,0,1]
	v_pk_fma_f32 v[198:199], v[186:187], v[198:199], v[88:89] op_sel:[1,0,0]
	v_fma_f32 v208, -v78, v186, v188
	v_pk_fma_f32 v[200:201], v[144:145], s[6:7], v[200:201] op_sel_hi:[1,0,1] neg_lo:[0,0,1] neg_hi:[0,0,1]
	v_pk_fma_f32 v[202:203], v[186:187], v[202:203], v[80:81] op_sel:[1,0,0]
	v_mul_f32_e32 v188, 0xbfb8aa3b, v199
	v_pk_fma_f32 v[200:201], v[186:187], v[200:201], v[82:83] op_sel:[1,0,0]
	v_mul_f32_e32 v185, 0xbfb8aa3b, v202
	v_exp_f32_e32 v188, v188
	v_fma_f32 v206, -v69, v186, v195
	v_mul_f32_e32 v195, 0xbfb8aa3b, v200
	v_exp_f32_e32 v185, v185
	v_exp_f32_e32 v195, v195
	v_fma_f32 v204, -v77, v186, v191
	v_mul_f32_e32 v177, 0xbfb8aa3b, v198
	v_mul_f32_e32 v191, 0xbfb8aa3b, v203
	v_exp_f32_e32 v177, v177
	v_exp_f32_e32 v191, v191
	v_add_f32_e32 v188, 1.0, v188
	v_pk_mul_f32 v[196:197], v[94:95], v[186:187] op_sel_hi:[1,0]
	v_add_f32_e32 v185, 1.0, v185
	v_rcp_f32_e32 v205, v188
	v_pk_fma_f32 v[196:197], v[148:149], s[6:7], v[196:197] op_sel_hi:[1,0,1] neg_lo:[0,0,1] neg_hi:[0,0,1]
	v_pk_mov_b32 v[218:219], v[186:187], v[200:201] op_sel:[1,0]
	v_add_f32_e32 v200, 1.0, v195
	v_rcp_f32_e32 v195, v185
	v_pk_fma_f32 v[196:197], v[186:187], v[196:197], v[90:91] op_sel:[1,0,0]
	v_fma_f32 v210, -v70, v186, v192
	v_pk_mov_b32 v[212:213], v[186:187], v[198:199] op_sel:[1,0]
	v_mov_b32_e32 v198, v187
	v_mul_f32_e32 v192, 0xbfb8aa3b, v196
	v_pk_mov_b32 v[216:217], v[186:187], v[196:197] op_sel:[1,0]
	v_add_f32_e32 v177, 1.0, v177
	v_add_f32_e32 v196, 1.0, v191
	v_fma_f32 v194, -v68, v186, v194
	v_pk_mov_b32 v[214:215], v[186:187], v[202:203] op_sel:[1,0]
	v_rcp_f32_e32 v191, v177
	v_rcp_f32_e32 v207, v196
	v_pk_mul_f32 v[198:199], v[198:199], v[204:205]
	v_pk_mul_f32 v[194:195], v[214:215], v[194:195]
	v_add_f32_e32 v188, v73, v198
	v_rcp_f32_e32 v211, v200
	v_add_f32_e32 v185, v64, v194
	v_mul_f32_e32 v194, v188, v199
	v_mul_f32_e32 v188, 0xbfb8aa3b, v197
	v_fma_f32 v190, -v76, v186, v190
	v_mov_b32_e32 v202, v187
	v_exp_f32_e32 v188, v188
	v_pk_mul_f32 v[190:191], v[212:213], v[190:191]
	v_pk_mul_f32 v[202:203], v[202:203], v[206:207]
	v_add_f32_e32 v177, v72, v190
	v_add_f32_e32 v190, v65, v202
	v_mul_f32_e32 v177, v177, v191
	v_mul_f32_e32 v185, v185, v195
	v_mul_f32_e32 v195, v190, v203
	v_pk_mul_f32 v[190:191], v[218:219], v[210:211]
	v_add_f32_e32 v188, 1.0, v188
	v_add_f32_e32 v190, v66, v190
	v_mul_f32_e32 v198, v190, v191
	v_rcp_f32_e32 v191, v188
	v_mul_f32_e32 v188, 0xbfb8aa3b, v201
	v_exp_f32_e32 v199, v188
	v_fma_f32 v190, -v79, v186, v189
	v_mov_b32_e32 v196, v187
	v_exp_f32_e32 v192, v192
	v_pk_mul_f32 v[188:189], v[196:197], v[190:191]
	v_add_f32_e32 v190, 1.0, v199
	v_rcp_f32_e32 v191, v190
	v_add_f32_e32 v192, 1.0, v192
	v_fma_f32 v190, -v71, v186, v193
	v_mov_b32_e32 v200, v187
	v_rcp_f32_e32 v209, v192
	v_pk_mul_f32 v[186:187], v[200:201], v[190:191]
	v_add_f32_e32 v188, v75, v188
	v_add_f32_e32 v186, v67, v186
	v_mul_f32_e32 v188, v188, v189
	v_mul_f32_e32 v189, v186, v187
	v_mul_f32_e32 v177, 0x41000000, v177
	v_mul_f32_e32 v187, 0x41000000, v194
	v_mov_b32_e32 v186, 0
	v_cvt_pk_fp8_f32 v186, v177, v187
	v_mul_f32_e32 v177, 0x41000000, v185
	v_mul_f32_e32 v185, 0x41000000, v195
	v_mov_b32_e32 v187, 0
	v_pk_mul_f32 v[204:205], v[216:217], v[208:209]
	v_cvt_pk_fp8_f32 v187, v177, v185
	v_add_f32_e32 v192, v74, v204
	v_mul_f32_e32 v192, v192, v205
	v_mul_f32_e32 v190, 0x41000000, v192
	v_mul_f32_e32 v188, 0x41000000, v188
	v_mul_f32_e32 v177, 0x41000000, v198
	v_mul_f32_e32 v185, 0x41000000, v189
	v_cvt_pk_fp8_f32 v186, v190, v188 op_sel:[0,0,1]
	v_cvt_pk_fp8_f32 v187, v177, v185 op_sel:[0,0,1]
	v_mad_i64_i32 v[184:185], s[24:25], v184, s82, v[178:179]
	v_lshl_add_u64 v[184:185], v[184:185], 0, v[174:175]
	global_store_dwordx2 v[184:185], v[186:187], off
	v_add_u32_e32 v184, 0x80, v176
	v_ashrrev_i32_e32 v185, 31, v184
	v_mov_b32_e32 v186, v226
	v_mov_b32_e32 v187, v227
	v_cvt_f32_i32_e32 v191, v61
	v_cvt_f32_i32_e32 v190, v60
	v_cvt_f32_i32_e32 v195, v57
	v_cvt_f32_i32_e32 v194, v56
	v_cvt_f32_i32_e32 v197, v29
	v_cvt_f32_i32_e32 v196, v28
	v_cvt_f32_i32_e32 v201, v25
	v_cvt_f32_i32_e32 v200, v24
	v_cvt_f32_i32_e32 v189, v63
	v_pk_mul_f32 v[196:197], v[196:197], s[6:7] op_sel_hi:[1,0]
	v_cvt_f32_i32_e32 v188, v62
	v_pk_mul_f32 v[200:201], v[200:201], s[6:7] op_sel_hi:[1,0]
	v_cvt_f32_i32_e32 v193, v59
	v_cvt_f32_i32_e32 v192, v58
	v_cvt_f32_i32_e32 v199, v31
	v_cvt_f32_i32_e32 v198, v30
	v_cvt_f32_i32_e32 v203, v27
	v_cvt_f32_i32_e32 v202, v26
	v_pk_mul_f32 v[198:199], v[198:199], s[6:7] op_sel_hi:[1,0]
	v_pk_mul_f32 v[202:203], v[202:203], s[6:7] op_sel_hi:[1,0]
	v_pk_mul_f32 v[206:207], v[92:93], v[186:187] op_sel_hi:[1,0]
	v_pk_mul_f32 v[210:211], v[84:85], v[186:187] op_sel_hi:[1,0]
	v_pk_fma_f32 v[190:191], v[190:191], s[6:7], v[206:207] op_sel_hi:[1,0,1] neg_lo:[0,0,1] neg_hi:[0,0,1]
	v_pk_fma_f32 v[194:195], v[194:195], s[6:7], v[210:211] op_sel_hi:[1,0,1] neg_lo:[0,0,1] neg_hi:[0,0,1]
	v_pk_fma_f32 v[190:191], v[186:187], v[190:191], v[88:89] op_sel:[1,0,0]
	v_pk_fma_f32 v[194:195], v[186:187], v[194:195], v[80:81] op_sel:[1,0,0]
	v_mul_f32_e32 v177, 0xbfb8aa3b, v190
	v_mul_f32_e32 v185, 0xbfb8aa3b, v194
	v_pk_mov_b32 v[206:207], v[186:187], v[194:195] op_sel:[1,0]
	v_mul_f32_e32 v194, 0xbfb8aa3b, v191
	v_exp_f32_e32 v194, v194
	v_fma_f32 v214, -v77, v186, v197
	v_mul_f32_e32 v197, 0xbfb8aa3b, v195
	v_exp_f32_e32 v177, v177
	v_exp_f32_e32 v197, v197
	v_add_f32_e32 v194, 1.0, v194
	v_rcp_f32_e32 v215, v194
	v_add_f32_e32 v177, 1.0, v177
	v_fma_f32 v212, -v68, v186, v200
	v_add_f32_e32 v200, 1.0, v197
	v_rcp_f32_e32 v197, v177
	v_pk_mul_f32 v[204:205], v[94:95], v[186:187] op_sel_hi:[1,0]
	v_pk_mul_f32 v[208:209], v[86:87], v[186:187] op_sel_hi:[1,0]
	v_pk_fma_f32 v[188:189], v[188:189], s[6:7], v[204:205] op_sel_hi:[1,0,1] neg_lo:[0,0,1] neg_hi:[0,0,1]
	v_pk_mov_b32 v[204:205], v[186:187], v[190:191] op_sel:[1,0]
	v_mov_b32_e32 v190, v187
	v_fma_f32 v196, -v76, v186, v196
	v_pk_mul_f32 v[190:191], v[190:191], v[214:215]
	v_pk_fma_f32 v[192:193], v[192:193], s[6:7], v[208:209] op_sel_hi:[1,0,1] neg_lo:[0,0,1] neg_hi:[0,0,1]
	v_pk_fma_f32 v[188:189], v[186:187], v[188:189], v[90:91] op_sel:[1,0,0]
	v_rcp_f32_e32 v209, v200
	v_pk_mul_f32 v[196:197], v[204:205], v[196:197]
	v_add_f32_e32 v190, v73, v190
	v_add_f32_e32 v177, v72, v196
	v_mul_f32_e32 v196, v190, v191
	v_mul_f32_e32 v190, 0xbfb8aa3b, v188
	v_mul_f32_e32 v177, v177, v197
	v_exp_f32_e32 v197, v190
	v_fma_f32 v208, -v69, v186, v201
	v_mov_b32_e32 v194, v187
	v_pk_mul_f32 v[190:191], v[194:195], v[208:209]
	v_pk_fma_f32 v[192:193], v[186:187], v[192:193], v[82:83] op_sel:[1,0,0]
	v_add_f32_e32 v190, v65, v190
	v_mul_f32_e32 v200, v190, v191
	v_add_f32_e32 v190, 1.0, v197
	v_rcp_f32_e32 v191, v190
	v_pk_mov_b32 v[194:195], v[186:187], v[188:189] op_sel:[1,0]
	v_mul_f32_e32 v188, 0xbfb8aa3b, v192
	v_exp_f32_e32 v188, v188
	v_fma_f32 v190, -v78, v186, v198
	v_pk_mul_f32 v[190:191], v[194:195], v[190:191]
	v_pk_mov_b32 v[194:195], v[186:187], v[192:193] op_sel:[1,0]
	v_add_f32_e32 v190, v74, v190
	v_add_f32_e32 v188, 1.0, v188
	v_mul_f32_e32 v197, v190, v191
	v_rcp_f32_e32 v191, v188
	v_mul_f32_e32 v188, 0xbfb8aa3b, v189
	v_exp_f32_e32 v188, v188
	v_fma_f32 v190, -v70, v186, v202
	v_pk_mul_f32 v[190:191], v[194:195], v[190:191]
	v_exp_f32_e32 v185, v185
	v_add_f32_e32 v190, v66, v190
	v_add_f32_e32 v188, 1.0, v188
	v_mul_f32_e32 v194, v190, v191
	v_rcp_f32_e32 v191, v188
	v_mul_f32_e32 v188, 0xbfb8aa3b, v193
	v_exp_f32_e32 v192, v188
	v_fma_f32 v190, -v79, v186, v199
	v_mov_b32_e32 v188, v187
	v_add_f32_e32 v185, 1.0, v185
	v_pk_mul_f32 v[188:189], v[188:189], v[190:191]
	v_add_f32_e32 v190, 1.0, v192
	v_rcp_f32_e32 v213, v185
	v_rcp_f32_e32 v191, v190
	v_fma_f32 v190, -v71, v186, v203
	v_mov_b32_e32 v192, v187
	v_pk_mul_f32 v[204:205], v[206:207], v[212:213]
	v_pk_mul_f32 v[186:187], v[192:193], v[190:191]
	v_add_f32_e32 v185, v64, v204
	v_add_f32_e32 v188, v75, v188
	v_add_f32_e32 v186, v67, v186
	v_mul_f32_e32 v185, v185, v205
	v_mul_f32_e32 v188, v188, v189
	v_mul_f32_e32 v189, v186, v187
	v_mul_f32_e32 v177, 0x41000000, v177
	v_mul_f32_e32 v187, 0x41000000, v196
	v_mov_b32_e32 v186, 0
	v_cvt_pk_fp8_f32 v186, v177, v187
	v_mul_f32_e32 v177, 0x41000000, v185
	v_mul_f32_e32 v185, 0x41000000, v200
	v_mov_b32_e32 v187, 0
	v_cvt_pk_fp8_f32 v187, v177, v185
	v_mul_f32_e32 v190, 0x41000000, v197
	v_mul_f32_e32 v188, 0x41000000, v188
	v_mul_f32_e32 v177, 0x41000000, v194
	v_mul_f32_e32 v185, 0x41000000, v189
	v_cvt_pk_fp8_f32 v186, v190, v188 op_sel:[0,0,1]
	v_cvt_pk_fp8_f32 v187, v177, v185 op_sel:[0,0,1]
	v_mad_i64_i32 v[184:185], s[24:25], v184, s82, v[178:179]
	v_lshl_add_u64 v[184:185], v[184:185], 0, v[174:175]
	global_store_dwordx2 v[184:185], v[186:187], off
	v_add_u32_e32 v184, 0x90, v176
	v_ashrrev_i32_e32 v185, 31, v184
	v_mov_b32_e32 v186, v228
	v_mov_b32_e32 v187, v229
	v_cvt_f32_i32_e32 v191, v53
	v_cvt_f32_i32_e32 v190, v52
	v_cvt_f32_i32_e32 v195, v49
	v_cvt_f32_i32_e32 v194, v48
	v_cvt_f32_i32_e32 v197, v21
	v_cvt_f32_i32_e32 v196, v20
	v_cvt_f32_i32_e32 v189, v55
	v_cvt_f32_i32_e32 v188, v54
	v_cvt_f32_i32_e32 v201, v17
	v_pk_mul_f32 v[196:197], v[196:197], s[6:7] op_sel_hi:[1,0]
	v_cvt_f32_i32_e32 v200, v16
	v_cvt_f32_i32_e32 v193, v51
	v_cvt_f32_i32_e32 v192, v50
	v_cvt_f32_i32_e32 v199, v23
	v_pk_mul_f32 v[200:201], v[200:201], s[6:7] op_sel_hi:[1,0]
	v_cvt_f32_i32_e32 v198, v22
	v_cvt_f32_i32_e32 v203, v19
	v_cvt_f32_i32_e32 v202, v18
	v_pk_mul_f32 v[198:199], v[198:199], s[6:7] op_sel_hi:[1,0]
	v_pk_mul_f32 v[202:203], v[202:203], s[6:7] op_sel_hi:[1,0]
	v_pk_mul_f32 v[206:207], v[92:93], v[186:187] op_sel_hi:[1,0]
	s_nop 0
	v_pk_fma_f32 v[190:191], v[190:191], s[6:7], v[206:207] op_sel_hi:[1,0,1] neg_lo:[0,0,1] neg_hi:[0,0,1]
	v_pk_mul_f32 v[210:211], v[84:85], v[186:187] op_sel_hi:[1,0]
	v_pk_fma_f32 v[190:191], v[186:187], v[190:191], v[88:89] op_sel:[1,0,0]
	v_pk_fma_f32 v[194:195], v[194:195], s[6:7], v[210:211] op_sel_hi:[1,0,1] neg_lo:[0,0,1] neg_hi:[0,0,1]
	v_mul_f32_e32 v177, 0xbfb8aa3b, v190
	v_exp_f32_e32 v177, v177
	v_pk_fma_f32 v[194:195], v[186:187], v[194:195], v[80:81] op_sel:[1,0,0]
	v_pk_mul_f32 v[204:205], v[94:95], v[186:187] op_sel_hi:[1,0]
	v_fma_f32 v212, -v76, v186, v196
	v_add_f32_e32 v177, 1.0, v177
	v_rcp_f32_e32 v213, v177
	v_mul_f32_e32 v177, 0xbfb8aa3b, v194
	v_exp_f32_e32 v177, v177
	v_pk_fma_f32 v[188:189], v[188:189], s[6:7], v[204:205] op_sel_hi:[1,0,1] neg_lo:[0,0,1] neg_hi:[0,0,1]
	v_pk_mov_b32 v[204:205], v[186:187], v[190:191] op_sel:[1,0]
	v_pk_mov_b32 v[206:207], v[186:187], v[194:195] op_sel:[1,0]
	v_pk_mul_f32 v[204:205], v[204:205], v[212:213]
	v_add_f32_e32 v177, 1.0, v177
	v_add_f32_e32 v185, v72, v204
	v_mul_f32_e32 v185, v185, v205
	v_rcp_f32_e32 v205, v177
	v_mul_f32_e32 v177, 0xbfb8aa3b, v191
	v_exp_f32_e32 v177, v177
	v_fma_f32 v204, -v68, v186, v200
	v_pk_mul_f32 v[204:205], v[206:207], v[204:205]
	v_pk_fma_f32 v[188:189], v[186:187], v[188:189], v[90:91] op_sel:[1,0,0]
	v_add_f32_e32 v190, v64, v204
	v_add_f32_e32 v177, 1.0, v177
	v_mul_f32_e32 v196, v190, v205
	v_rcp_f32_e32 v205, v177
	v_mul_f32_e32 v177, 0xbfb8aa3b, v195
	v_exp_f32_e32 v177, v177
	v_fma_f32 v204, -v77, v186, v197
	v_mov_b32_e32 v190, v187
	v_pk_mul_f32 v[190:191], v[190:191], v[204:205]
	v_add_f32_e32 v177, 1.0, v177
	v_add_f32_e32 v190, v73, v190
	v_mul_f32_e32 v197, v190, v191
	v_rcp_f32_e32 v191, v177
	v_mul_f32_e32 v177, 0xbfb8aa3b, v188
	v_exp_f32_e32 v177, v177
	v_pk_mul_f32 v[208:209], v[86:87], v[186:187] op_sel_hi:[1,0]
	v_fma_f32 v190, -v69, v186, v201
	v_mov_b32_e32 v194, v187
	v_pk_fma_f32 v[192:193], v[192:193], s[6:7], v[208:209] op_sel_hi:[1,0,1] neg_lo:[0,0,1] neg_hi:[0,0,1]
	v_pk_mul_f32 v[190:191], v[194:195], v[190:191]
	v_pk_fma_f32 v[192:193], v[186:187], v[192:193], v[82:83] op_sel:[1,0,0]
	v_add_f32_e32 v190, v65, v190
	v_add_f32_e32 v177, 1.0, v177
	v_mul_f32_e32 v200, v190, v191
	v_rcp_f32_e32 v191, v177
	v_mul_f32_e32 v177, 0xbfb8aa3b, v192
	v_exp_f32_e32 v177, v177
	v_fma_f32 v190, -v78, v186, v198
	v_pk_mov_b32 v[194:195], v[186:187], v[188:189] op_sel:[1,0]
	v_mul_f32_e32 v185, 0x41000000, v185
	v_pk_mul_f32 v[190:191], v[194:195], v[190:191]
	v_add_f32_e32 v177, 1.0, v177
	v_add_f32_e32 v188, v74, v190
	v_mul_f32_e32 v198, v188, v191
	v_rcp_f32_e32 v191, v177
	v_mul_f32_e32 v177, 0xbfb8aa3b, v189
	v_exp_f32_e32 v177, v177
	v_fma_f32 v190, -v70, v186, v202
	v_pk_mov_b32 v[194:195], v[186:187], v[192:193] op_sel:[1,0]
	v_mov_b32_e32 v192, v187
	v_pk_mul_f32 v[190:191], v[194:195], v[190:191]
	v_add_f32_e32 v177, 1.0, v177
	v_add_f32_e32 v188, v66, v190
	v_mul_f32_e32 v194, v188, v191
	v_rcp_f32_e32 v191, v177
	v_mul_f32_e32 v177, 0xbfb8aa3b, v193
	v_exp_f32_e32 v177, v177
	v_fma_f32 v190, -v79, v186, v199
	v_mov_b32_e32 v188, v187
	v_pk_mul_f32 v[188:189], v[188:189], v[190:191]
	v_add_f32_e32 v177, 1.0, v177
	v_rcp_f32_e32 v191, v177
	v_fma_f32 v190, -v71, v186, v203
	v_add_f32_e32 v188, v75, v188
	v_mul_f32_e32 v177, v188, v189
	v_pk_mul_f32 v[186:187], v[192:193], v[190:191]
	v_mul_f32_e32 v190, 0x41000000, v200
	v_add_f32_e32 v186, v67, v186
	v_mul_f32_e32 v188, v186, v187
	v_mul_f32_e32 v187, 0x41000000, v197
	v_mov_b32_e32 v186, 0
	v_cvt_pk_fp8_f32 v186, v185, v187
	v_mul_f32_e32 v185, 0x41000000, v196
	v_mov_b32_e32 v187, 0
	v_cvt_pk_fp8_f32 v187, v185, v190
	v_mul_f32_e32 v189, 0x41000000, v198
	v_mul_f32_e32 v177, 0x41000000, v177
	v_cvt_pk_fp8_f32 v186, v189, v177 op_sel:[0,0,1]
	v_mul_f32_e32 v177, 0x41000000, v194
	v_mul_f32_e32 v185, 0x41000000, v188
	v_cvt_pk_fp8_f32 v187, v177, v185 op_sel:[0,0,1]
	v_mad_i64_i32 v[184:185], s[24:25], v184, s82, v[178:179]
	v_lshl_add_u64 v[184:185], v[184:185], 0, v[174:175]
	global_store_dwordx2 v[184:185], v[186:187], off
	v_add_u32_e32 v184, 0xa0, v176
	v_ashrrev_i32_e32 v185, 31, v184
	v_mov_b32_e32 v186, v230
	v_mov_b32_e32 v187, v231
	v_cvt_f32_i32_e32 v191, v45
	v_cvt_f32_i32_e32 v190, v44
	v_cvt_f32_i32_e32 v201, v9
	v_cvt_f32_i32_e32 v200, v8
	v_cvt_f32_i32_e32 v189, v47
	v_cvt_f32_i32_e32 v188, v46
	v_cvt_f32_i32_e32 v203, v11
	v_pk_mul_f32 v[200:201], v[200:201], s[6:7] op_sel_hi:[1,0]
	v_cvt_f32_i32_e32 v202, v10
	v_add_u32_e32 v176, 0xb0, v176
	v_pk_mul_f32 v[202:203], v[202:203], s[6:7] op_sel_hi:[1,0]
	v_pk_mul_f32 v[194:195], v[92:93], v[186:187] op_sel_hi:[1,0]
	s_nop 0
	v_pk_fma_f32 v[190:191], v[190:191], s[6:7], v[194:195] op_sel_hi:[1,0,1] neg_lo:[0,0,1] neg_hi:[0,0,1]
	v_cvt_f32_i32_e32 v195, v41
	v_pk_fma_f32 v[190:191], v[186:187], v[190:191], v[88:89] op_sel:[1,0,0]
	v_cvt_f32_i32_e32 v194, v40
	v_mul_f32_e32 v177, 0xbfb8aa3b, v190
	v_exp_f32_e32 v177, v177
	v_pk_mul_f32 v[198:199], v[84:85], v[186:187] op_sel_hi:[1,0]
	v_pk_mov_b32 v[206:207], v[186:187], v[190:191] op_sel:[1,0]
	v_pk_fma_f32 v[194:195], v[194:195], s[6:7], v[198:199] op_sel_hi:[1,0,1] neg_lo:[0,0,1] neg_hi:[0,0,1]
	v_cvt_f32_i32_e32 v199, v13
	v_cvt_f32_i32_e32 v198, v12
	v_pk_fma_f32 v[194:195], v[186:187], v[194:195], v[80:81] op_sel:[1,0,0]
	v_add_f32_e32 v177, 1.0, v177
	v_rcp_f32_e32 v205, v177
	v_mul_f32_e32 v177, 0xbfb8aa3b, v194
	v_exp_f32_e32 v177, v177
	v_pk_mul_f32 v[198:199], v[198:199], s[6:7] op_sel_hi:[1,0]
	v_pk_mul_f32 v[192:193], v[94:95], v[186:187] op_sel_hi:[1,0]
	v_fma_f32 v204, -v76, v186, v198
	v_pk_mul_f32 v[204:205], v[206:207], v[204:205]
	v_add_f32_e32 v177, 1.0, v177
	v_add_f32_e32 v185, v72, v204
	v_mul_f32_e32 v185, v185, v205
	v_rcp_f32_e32 v205, v177
	v_mul_f32_e32 v177, 0xbfb8aa3b, v191
	v_exp_f32_e32 v177, v177
	v_fma_f32 v204, -v68, v186, v200
	v_pk_mov_b32 v[206:207], v[186:187], v[194:195] op_sel:[1,0]
	v_pk_fma_f32 v[188:189], v[188:189], s[6:7], v[192:193] op_sel_hi:[1,0,1] neg_lo:[0,0,1] neg_hi:[0,0,1]
	v_pk_mul_f32 v[204:205], v[206:207], v[204:205]
	v_add_f32_e32 v177, 1.0, v177
	v_add_f32_e32 v190, v64, v204
	v_mul_f32_e32 v198, v190, v205
	v_rcp_f32_e32 v205, v177
	v_mul_f32_e32 v177, 0xbfb8aa3b, v195
	v_exp_f32_e32 v177, v177
	v_fma_f32 v204, -v77, v186, v199
	v_mov_b32_e32 v190, v187
	v_pk_mul_f32 v[190:191], v[190:191], v[204:205]
	v_pk_fma_f32 v[188:189], v[186:187], v[188:189], v[90:91] op_sel:[1,0,0]
	v_add_f32_e32 v190, v73, v190
	v_add_f32_e32 v177, 1.0, v177
	v_cvt_f32_i32_e32 v193, v43
	v_cvt_f32_i32_e32 v192, v42
	v_mul_f32_e32 v199, v190, v191
	v_rcp_f32_e32 v191, v177
	v_mul_f32_e32 v177, 0xbfb8aa3b, v188
	v_exp_f32_e32 v177, v177
	v_pk_mul_f32 v[196:197], v[86:87], v[186:187] op_sel_hi:[1,0]
	v_fma_f32 v190, -v69, v186, v201
	v_mov_b32_e32 v194, v187
	v_pk_fma_f32 v[192:193], v[192:193], s[6:7], v[196:197] op_sel_hi:[1,0,1] neg_lo:[0,0,1] neg_hi:[0,0,1]
	v_cvt_f32_i32_e32 v197, v15
	v_cvt_f32_i32_e32 v196, v14
	v_pk_mul_f32 v[190:191], v[194:195], v[190:191]
	v_pk_fma_f32 v[192:193], v[186:187], v[192:193], v[82:83] op_sel:[1,0,0]
	v_add_f32_e32 v190, v65, v190
	v_add_f32_e32 v177, 1.0, v177
	v_mul_f32_e32 v200, v190, v191
	v_rcp_f32_e32 v191, v177
	v_mul_f32_e32 v177, 0xbfb8aa3b, v192
	v_exp_f32_e32 v177, v177
	v_pk_mul_f32 v[196:197], v[196:197], s[6:7] op_sel_hi:[1,0]
	v_pk_mov_b32 v[194:195], v[186:187], v[188:189] op_sel:[1,0]
	v_fma_f32 v190, -v78, v186, v196
	v_pk_mul_f32 v[190:191], v[194:195], v[190:191]
	v_add_f32_e32 v177, 1.0, v177
	v_add_f32_e32 v188, v74, v190
	v_mul_f32_e32 v196, v188, v191
	v_rcp_f32_e32 v191, v177
	v_mul_f32_e32 v177, 0xbfb8aa3b, v189
	v_exp_f32_e32 v177, v177
	v_fma_f32 v190, -v70, v186, v202
	v_pk_mov_b32 v[194:195], v[186:187], v[192:193] op_sel:[1,0]
	v_mov_b32_e32 v192, v187
	v_pk_mul_f32 v[190:191], v[194:195], v[190:191]
	v_add_f32_e32 v177, 1.0, v177
	v_add_f32_e32 v188, v66, v190
	v_mul_f32_e32 v194, v188, v191
	v_rcp_f32_e32 v191, v177
	v_mul_f32_e32 v177, 0xbfb8aa3b, v193
	v_exp_f32_e32 v177, v177
	v_fma_f32 v190, -v79, v186, v197
	v_mov_b32_e32 v188, v187
	v_pk_mul_f32 v[188:189], v[188:189], v[190:191]
	v_add_f32_e32 v177, 1.0, v177
	v_rcp_f32_e32 v191, v177
	v_fma_f32 v190, -v71, v186, v203
	v_add_f32_e32 v188, v75, v188
	v_mul_f32_e32 v177, v188, v189
	v_pk_mul_f32 v[186:187], v[192:193], v[190:191]
	v_mul_f32_e32 v185, 0x41000000, v185
	v_add_f32_e32 v186, v67, v186
	v_mul_f32_e32 v188, v186, v187
	v_mul_f32_e32 v187, 0x41000000, v199
	v_mov_b32_e32 v186, 0
	v_cvt_pk_fp8_f32 v186, v185, v187
	v_mul_f32_e32 v185, 0x41000000, v198
	v_mul_f32_e32 v190, 0x41000000, v200
	v_mov_b32_e32 v187, 0
	v_cvt_pk_fp8_f32 v187, v185, v190
	v_mul_f32_e32 v189, 0x41000000, v196
	v_mul_f32_e32 v177, 0x41000000, v177
	v_cvt_pk_fp8_f32 v186, v189, v177 op_sel:[0,0,1]
	v_mul_f32_e32 v177, 0x41000000, v194
	v_mul_f32_e32 v185, 0x41000000, v188
	v_cvt_pk_fp8_f32 v187, v177, v185 op_sel:[0,0,1]
	v_mad_i64_i32 v[184:185], s[24:25], v184, s82, v[178:179]
	v_lshl_add_u64 v[184:185], v[184:185], 0, v[174:175]
	v_ashrrev_i32_e32 v177, 31, v176
	global_store_dwordx2 v[184:185], v[186:187], off
	v_mov_b32_e32 v184, v232
	v_mov_b32_e32 v185, v233
	v_cvt_f32_i32_e32 v187, v39
	v_cvt_f32_i32_e32 v186, v38
	v_cvt_f32_i32_e32 v189, v37
	v_cvt_f32_i32_e32 v188, v36
	v_pk_mul_f32 v[94:95], v[94:95], v[184:185] op_sel_hi:[1,0]
	s_nop 0
	v_pk_fma_f32 v[94:95], v[186:187], s[6:7], v[94:95] op_sel_hi:[1,0,1] neg_lo:[0,0,1] neg_hi:[0,0,1]
	v_pk_mul_f32 v[92:93], v[92:93], v[184:185] op_sel_hi:[1,0]
	v_pk_fma_f32 v[90:91], v[184:185], v[94:95], v[90:91] op_sel:[1,0,0]
	v_cvt_f32_i32_e32 v95, v33
	v_cvt_f32_i32_e32 v94, v32
	v_pk_fma_f32 v[92:93], v[188:189], s[6:7], v[92:93] op_sel_hi:[1,0,1] neg_lo:[0,0,1] neg_hi:[0,0,1]
	v_pk_mul_f32 v[84:85], v[84:85], v[184:185] op_sel_hi:[1,0]
	v_pk_fma_f32 v[88:89], v[184:185], v[92:93], v[88:89] op_sel:[1,0,0]
	v_pk_fma_f32 v[84:85], v[94:95], s[6:7], v[84:85] op_sel_hi:[1,0,1] neg_lo:[0,0,1] neg_hi:[0,0,1]
	v_mul_f32_e32 v177, 0xbfb8aa3b, v88
	v_exp_f32_e32 v177, v177
	v_pk_fma_f32 v[80:81], v[184:185], v[84:85], v[80:81] op_sel:[1,0,0]
	v_cvt_f32_i32_e32 v85, v5
	v_cvt_f32_i32_e32 v84, v4
	v_cvt_f32_i32_e32 v93, v35
	v_cvt_f32_i32_e32 v92, v34
	v_add_f32_e32 v177, 1.0, v177
	v_pk_mul_f32 v[84:85], v[84:85], s[6:7] op_sel_hi:[1,0]
	v_rcp_f32_e32 v187, v177
	v_fma_f32 v186, -v76, v184, v84
	v_mul_f32_e32 v76, 0xbfb8aa3b, v80
	v_pk_mul_f32 v[86:87], v[86:87], v[184:185] op_sel_hi:[1,0]
	v_exp_f32_e32 v76, v76
	v_pk_fma_f32 v[86:87], v[92:93], s[6:7], v[86:87] op_sel_hi:[1,0,1] neg_lo:[0,0,1] neg_hi:[0,0,1]
	v_cvt_f32_i32_e32 v93, v1
	v_cvt_f32_i32_e32 v92, v0
	v_pk_mov_b32 v[188:189], v[184:185], v[88:89] op_sel:[1,0]
	v_mov_b32_e32 v88, v185
	v_pk_mul_f32 v[186:187], v[188:189], v[186:187]
	v_pk_mul_f32 v[92:93], v[92:93], s[6:7] op_sel_hi:[1,0]
	v_add_f32_e32 v72, v72, v186
	v_mul_f32_e32 v84, v72, v187
	v_add_f32_e32 v72, 1.0, v76
	v_rcp_f32_e32 v187, v72
	v_fma_f32 v186, -v68, v184, v92
	v_mul_f32_e32 v68, 0xbfb8aa3b, v89
	v_exp_f32_e32 v68, v68
	v_pk_mov_b32 v[188:189], v[184:185], v[80:81] op_sel:[1,0]
	v_fma_f32 v72, -v69, v184, v93
	v_pk_mul_f32 v[186:187], v[188:189], v[186:187]
	v_mov_b32_e32 v80, v185
	v_add_f32_e32 v64, v64, v186
	v_mul_f32_e32 v92, v64, v187
	v_add_f32_e32 v64, 1.0, v68
	v_rcp_f32_e32 v187, v64
	v_mul_f32_e32 v64, 0xbfb8aa3b, v81
	v_exp_f32_e32 v64, v64
	v_fma_f32 v186, -v77, v184, v85
	v_pk_mul_f32 v[76:77], v[88:89], v[186:187]
	v_pk_fma_f32 v[82:83], v[184:185], v[86:87], v[82:83] op_sel:[1,0,0]
	v_add_f32_e32 v64, 1.0, v64
	v_add_f32_e32 v68, v73, v76
	v_rcp_f32_e32 v73, v64
	v_mul_f32_e32 v64, 0xbfb8aa3b, v90
	v_exp_f32_e32 v64, v64
	v_cvt_f32_i32_e32 v87, v7
	v_cvt_f32_i32_e32 v86, v6
	v_mul_f32_e32 v76, v68, v77
	v_pk_mul_f32 v[68:69], v[80:81], v[72:73]
	v_add_f32_e32 v64, 1.0, v64
	v_add_f32_e32 v65, v65, v68
	v_mul_f32_e32 v72, v65, v69
	v_rcp_f32_e32 v65, v64
	v_mul_f32_e32 v73, 0xbfb8aa3b, v82
	v_pk_mul_f32 v[86:87], v[86:87], s[6:7] op_sel_hi:[1,0]
	v_exp_f32_e32 v73, v73
	v_fma_f32 v64, -v78, v184, v86
	v_pk_mov_b32 v[68:69], v[184:185], v[90:91] op_sel:[1,0]
	v_cvt_f32_i32_e32 v95, v3
	v_cvt_f32_i32_e32 v94, v2
	v_pk_mul_f32 v[64:65], v[68:69], v[64:65]
	v_pk_mov_b32 v[68:69], v[184:185], v[82:83] op_sel:[1,0]
	v_add_f32_e32 v64, v74, v64
	v_mul_f32_e32 v74, v64, v65
	v_add_f32_e32 v64, 1.0, v73
	v_rcp_f32_e32 v65, v64
	v_pk_mul_f32 v[94:95], v[94:95], s[6:7] op_sel_hi:[1,0]
	v_mov_b32_e32 v90, v185
	v_fma_f32 v64, -v70, v184, v94
	v_mul_f32_e32 v70, 0xbfb8aa3b, v91
	v_exp_f32_e32 v70, v70
	v_pk_mul_f32 v[64:65], v[68:69], v[64:65]
	v_mul_f32_e32 v68, 0xbfb8aa3b, v83
	v_exp_f32_e32 v68, v68
	v_add_f32_e32 v64, v66, v64
	v_mul_f32_e32 v66, v64, v65
	v_add_f32_e32 v64, 1.0, v70
	v_rcp_f32_e32 v65, v64
	v_add_f32_e32 v68, 1.0, v68
	v_rcp_f32_e32 v69, v68
	v_fma_f32 v64, -v79, v184, v87
	v_pk_mul_f32 v[64:65], v[90:91], v[64:65]
	v_fma_f32 v68, -v71, v184, v95
	v_add_f32_e32 v64, v75, v64
	v_mov_b32_e32 v82, v185
	v_mul_f32_e32 v70, v64, v65
	v_pk_mul_f32 v[64:65], v[82:83], v[68:69]
	v_mul_f32_e32 v68, 0x41000000, v76
	v_add_f32_e32 v64, v67, v64
	v_mul_f32_e32 v67, v64, v65
	v_mul_f32_e32 v65, 0x41000000, v84
	v_mov_b32_e32 v64, 0
	v_cvt_pk_fp8_f32 v64, v65, v68
	v_mul_f32_e32 v68, 0x41000000, v92
	v_mul_f32_e32 v71, 0x41000000, v72
	v_mov_b32_e32 v65, 0
	v_cvt_pk_fp8_f32 v65, v68, v71
	v_mul_f32_e32 v69, 0x41000000, v74
	v_mul_f32_e32 v70, 0x41000000, v70
	v_mul_f32_e32 v66, 0x41000000, v66
	v_mul_f32_e32 v67, 0x41000000, v67
	v_cvt_pk_fp8_f32 v64, v69, v70 op_sel:[0,0,1]
	v_cvt_pk_fp8_f32 v65, v66, v67 op_sel:[0,0,1]
	v_mad_i64_i32 v[66:67], s[24:25], v176, s82, v[178:179]
	v_lshl_add_u64 v[66:67], v[66:67], 0, v[174:175]
	global_store_dwordx2 v[66:67], v[64:65], off
	s_cbranch_execz .LBB0_1317
